# barrier spin loops: s_sleep 3 instead of s_sleep 1 between polls (less polling traffic on the flag)
# speedup vs baseline: 1.0051x; 1.0051x over previous
; __global__ void __launch_bounds__(256, 2) mk_fwd(Params p_in) {
;     ...
;   if (p.ph_lo < 0) cg::this_grid().sync();
.LBB0_12:
	s_sleep 3
	global_load_dword v2, v0, s[2:3] offset:32 sc1
	s_waitcnt vmcnt(0)
	v_and_b32_e32 v2, 0xffff0000, v2
	v_cmp_ne_u32_e32 vcc, v2, v1
	s_or_b64 s[4:5], vcc, s[4:5]
	s_andn2_b64 exec, exec, s[4:5]
	s_cbranch_execnz .LBB0_12

; DI unsigned xb_ld(unsigned* p) { return __hip_atomic_load(p, __ATOMIC_RELAXED, __HIP_MEMORY_SCOPE_AGENT); }
; DI void xcd_barrier_complete(unsigned* bar, unsigned x, unsigned& nloc, unsigned& nx) {
;     ...
;   for (;;) {
;     sum = 0u; cnt = 0u; mine = 0u;
; #pragma unroll
;     for (unsigned j = 0; j < 16; ++j) { const unsigned c = xb_ld(&bar[XB_XCNT(j)]); sum += c; cnt += (c > 0u) ? 1u : 0u; mine = (j == x) ? c : mine; }
;     if (sum == G) break;
;     __builtin_amdgcn_s_sleep(1);
;     if ((++sp & 255u) == 0u) { if (xb_ld(&bar[XB_TMO])) break; if (sp > XB_SPIN_CAP) { atomicAdd(&bar[XB_TMO], 1u); break; } }
;   }
.LBB0_67:
	global_load_dword v25, v[0:1], off offset:1024 sc1
	global_load_dword v10, v[0:1], off offset:1280 sc1
	global_load_dword v11, v[0:1], off offset:1536 sc1
	global_load_dword v12, v[0:1], off offset:1792 sc1
	global_load_dword v13, v[0:1], off offset:2048 sc1
	global_load_dword v14, v[0:1], off offset:2304 sc1
	global_load_dword v15, v[0:1], off offset:2560 sc1
	global_load_dword v16, v[0:1], off offset:2816 sc1
	global_load_dword v17, v[0:1], off offset:3072 sc1
	global_load_dword v18, v[0:1], off offset:3328 sc1
	global_load_dword v19, v[0:1], off offset:3584 sc1
	global_load_dword v20, v[0:1], off offset:3840 sc1
	global_load_dword v21, v[2:3], off sc1
	global_load_dword v22, v[4:5], off sc1
	global_load_dword v23, v[6:7], off sc1
	global_load_dword v24, v[8:9], off sc1
	s_or_b64 s[8:9], s[8:9], exec
	s_or_b64 s[6:7], s[6:7], exec
	s_waitcnt vmcnt(0) lgkmcnt(0)
	v_add_u32_e32 v26, v10, v25
	v_add_u32_e32 v26, v26, v11
	v_add_u32_e32 v26, v26, v12
	v_add_u32_e32 v26, v26, v13
	v_add_u32_e32 v26, v26, v14
	v_add_u32_e32 v26, v26, v15
	v_add_u32_e32 v26, v26, v16
	v_add_u32_e32 v26, v26, v17
	v_add_u32_e32 v26, v26, v18
	v_add_u32_e32 v26, v26, v19
	v_add_u32_e32 v26, v26, v20
	v_add_u32_e32 v26, v26, v21
	v_add_u32_e32 v26, v26, v22
	v_add_u32_e32 v26, v26, v23
	v_add_u32_e32 v26, v26, v24
	v_cmp_ne_u32_e32 vcc, s54, v26
	s_and_saveexec_b64 s[10:11], vcc
	s_cbranch_execz .LBB0_66
	s_and_b32 s14, s20, 0xff
	s_mov_b64 s[12:13], -1
	s_cmp_eq_u32 s14, 0
	s_mov_b64 s[16:17], -1
	s_mov_b64 s[14:15], -1
	s_sleep 3
	s_cbranch_scc1 .LBB0_70
	s_and_saveexec_b64 s[18:19], s[16:17]
	s_cbranch_execz .LBB0_65
	s_branch .LBB0_73

.LBB0_80:
	s_and_b32 s16, s23, 0xff
	s_mov_b64 s[14:15], -1
	s_cmp_lg_u32 s16, 0
	s_mov_b64 s[16:17], -1
	s_sleep 3
	s_cbranch_scc1 .LBB0_84
	v_mov_b64_e32 v[2:3], s[36:37]
	global_load_dword v1, v[2:3], off sc1
	s_mov_b64 s[16:17], 0
	s_mov_b64 s[18:19], -1
	s_waitcnt vmcnt(0) lgkmcnt(0)
	v_cmp_eq_u32_e32 vcc, 0, v1
	s_and_saveexec_b64 s[20:21], vcc
	s_cmp_lt_u32 s23, 0x400001
	s_cselect_b64 s[16:17], -1, 0
	s_xor_b64 s[18:19], exec, -1
	s_and_b64 s[16:17], s[16:17], exec
	s_or_b64 exec, exec, s[20:21]

.LBB0_94:
	s_and_b32 s12, s20, 0xff
	s_cmp_lg_u32 s12, 0
	s_mov_b64 s[14:15], -1
	s_sleep 3
	s_cbranch_scc0 .LBB0_96
	s_mov_b64 s[16:17], -1
	s_and_saveexec_b64 s[18:19], s[14:15]
	s_cbranch_execz .LBB0_93
	s_branch .LBB0_99

.LBB0_130:
	s_and_b32 s22, s2, 0xff
	s_mov_b64 s[20:21], -1
	s_cmp_lg_u32 s22, 0
	s_mov_b64 s[22:23], -1
	s_sleep 3
	s_cbranch_scc1 .LBB0_134
	v_mov_b64_e32 v[2:3], s[4:5]
	global_load_dword v1, v[2:3], off offset:512 sc1
	s_mov_b64 s[22:23], 0
	s_mov_b64 s[24:25], -1
	s_waitcnt vmcnt(0) lgkmcnt(0)
	v_cmp_eq_u32_e32 vcc, 0, v1
	s_and_saveexec_b64 s[26:27], vcc
	s_cmp_lt_u32 s2, 0x400001
	s_cselect_b64 s[22:23], -1, 0
	s_xor_b64 s[24:25], exec, -1
	s_and_b64 s[22:23], s[22:23], exec
	s_or_b64 exec, exec, s[26:27]

.LBB0_144:
	s_and_b32 s22, s2, 0xff
	s_mov_b64 s[20:21], -1
	s_cmp_lg_u32 s22, 0
	s_mov_b64 s[24:25], -1
	s_sleep 3
	s_cbranch_scc0 .LBB0_146
	s_and_saveexec_b64 s[26:27], s[24:25]
	s_cbranch_execz .LBB0_143
	s_branch .LBB0_149
